# v132 with XCD-local barrier arrival loops spinning without s_sleep
# baseline (speedup 1.0000x reference)
.LBB0_15:
	v_readlane_b32 s2, v251, 9
	v_readlane_b32 s3, v251, 10
	s_mov_b64 s[22:23], -1
	s_nop 3
	global_load_dword v0, v1, s[2:3] sc1
	v_readlane_b32 s2, v251, 11
	v_readlane_b32 s3, v251, 12
	s_nop 4
	global_load_dword v2, v1, s[2:3] sc1
	v_readlane_b32 s2, v251, 13
	v_readlane_b32 s3, v251, 14
	s_nop 1
	s_nop 2
	global_load_dword v3, v1, s[2:3] sc1
	v_readlane_b32 s2, v251, 15
	v_readlane_b32 s3, v251, 16
	s_nop 1
	s_nop 2
	global_load_dword v4, v1, s[2:3] sc1
	v_readlane_b32 s2, v251, 17
	v_readlane_b32 s3, v251, 18
	s_nop 1
	s_nop 2
	global_load_dword v5, v1, s[2:3] sc1
	v_readlane_b32 s2, v251, 19
	v_readlane_b32 s3, v251, 20
	s_nop 1
	s_nop 2
	global_load_dword v6, v1, s[2:3] sc1
	v_readlane_b32 s2, v251, 21
	v_readlane_b32 s3, v251, 22
	s_nop 1
	s_nop 2
	global_load_dword v7, v1, s[2:3] sc1
	v_readlane_b32 s2, v251, 23
	v_readlane_b32 s3, v251, 24
	s_nop 1
	s_nop 2
	global_load_dword v8, v1, s[2:3] sc1
	v_readlane_b32 s2, v251, 25
	v_readlane_b32 s3, v251, 26
	s_nop 1
	s_nop 2
	global_load_dword v9, v1, s[2:3] sc1
	v_readlane_b32 s2, v251, 27
	v_readlane_b32 s3, v251, 28
	s_nop 1
	s_nop 2
	global_load_dword v10, v1, s[2:3] sc1
	v_readlane_b32 s2, v251, 29
	v_readlane_b32 s3, v251, 30
	s_nop 1
	s_nop 2
	global_load_dword v11, v1, s[2:3] sc1
	v_readlane_b32 s2, v251, 31
	v_readlane_b32 s3, v251, 32
	s_nop 1
	s_nop 2
	global_load_dword v12, v1, s[2:3] sc1
	v_readlane_b32 s2, v251, 33
	v_readlane_b32 s3, v251, 34
	s_nop 1
	s_nop 2
	global_load_dword v13, v1, s[2:3] sc1
	v_readlane_b32 s2, v251, 35
	v_readlane_b32 s3, v251, 36
	s_nop 1
	s_nop 2
	global_load_dword v14, v1, s[2:3] sc1
	v_readlane_b32 s2, v251, 37
	v_readlane_b32 s3, v251, 38
	s_nop 1
	s_nop 2
	global_load_dword v15, v1, s[2:3] sc1
	v_readlane_b32 s2, v251, 39
	v_readlane_b32 s3, v251, 40
	s_nop 1
	s_nop 2
	global_load_dword v16, v1, s[2:3] sc1
	s_mov_b64 s[2:3], -1
	s_waitcnt vmcnt(0)
	v_add_u32_e32 v17, v2, v0
	v_add_u32_e32 v17, v17, v3
	v_add_u32_e32 v17, v17, v4
	v_add_u32_e32 v17, v17, v5
	v_add_u32_e32 v17, v17, v6
	v_add_u32_e32 v17, v17, v7
	v_add_u32_e32 v17, v17, v8
	v_add_u32_e32 v17, v17, v9
	v_add_u32_e32 v17, v17, v10
	v_add_u32_e32 v17, v17, v11
	v_add_u32_e32 v17, v17, v12
	v_add_u32_e32 v17, v17, v13
	v_add_u32_e32 v17, v17, v14
	v_add_u32_e32 v17, v17, v15
	v_add_u32_e32 v17, v17, v16
	v_cmp_eq_u32_e32 vcc, s4, v17
	s_cbranch_vccnz .LBB0_14
	s_and_b32 s2, s5, 0xff
	s_cmp_eq_u32 s2, 0
	s_mov_b64 s[2:3], -1
	s_mov_b64 s[24:25], -1
	s_nop 0
	s_cbranch_scc1 .LBB0_19
	s_and_b64 vcc, exec, s[24:25]
	s_cbranch_vccz .LBB0_14

.LBB0_33:
	s_and_b32 s5, s4, 0xff
	s_mov_b64 s[30:31], -1
	s_cmp_lg_u32 s5, 0
	s_mov_b64 s[36:37], -1
	s_nop 0
	s_cbranch_scc0 .LBB0_36
	s_and_b64 vcc, exec, s[36:37]
	s_cbranch_vccz .LBB0_32
